# baseline (speedup 1.0000x reference)
; __global__ __launch_bounds__(512, 2)
; void hybrid_megakernel(Params p_in) {
;     ...
;         for (int t = bid; t < ngt; t += G) {
;           const GemmArgs g = load_desc(dt + t);
.LBB0_42:
	s_add_i32 s0, s8, s52
	s_cmp_ge_i32 s0, s38
	s_cbranch_scc1 .Lpf_skip
	s_ashr_i32 s1, s0, 31
	s_lshl_b64 s[0:1], s[0:1], 6
	s_add_u32 s0, s57, s0
	s_addc_u32 s1, s61, s1
	s_load_dwordx16 s[84:99], s[0:1], 0x0

; __device__ __forceinline__ unsigned rfl(unsigned v) { return (unsigned)__builtin_amdgcn_readfirstlane((int)v); }
; __global__ __launch_bounds__(512, 2)
; void hybrid_megakernel(Params p_in) {
;     ...
;           const float slope = exp2f(-(float)(h + 1));
;           const float q2 = __uint_as_float(rfl(nrm[b * 32 + h * 2 + c])), k2 = __uint_as_float(rfl(nrm[b * 32 + 16 + h * 2 + c]));
;           const float Bnd = sqrtf(q2 * k2) * ASCALE * 1.002f + 0.05f;
;           const float nsf = __uint_as_float(rfl(((const unsigned*)(ws + WS_NRM))[144 + l * (NB * 16) + b * 16 + h * 2 + c]));
;           const float lowb = fminf(nsf * ASCALE * 1.002f + 0.05f, Bnd);
.LBB0_157:
	s_sub_i32 s0, 8, s8
	v_cvt_f32_i32_e32 v0, s0
	s_mov_b32 s0, 0x42fc0000
	v_mov_b32_e32 v1, 0x42800000
	s_and_b32 s63, s9, 1
	v_cmp_lt_f32_e32 vcc, s0, v0
	s_sub_i32 s1, 7, s8
	s_and_b64 s[8:9], vcc, exec
	v_cndmask_b32_e32 v1, 0, v1, vcc
	v_sub_f32_e32 v0, v1, v0
	v_exp_f32_e32 v0, v0
	s_cselect_b32 s0, 0xffffffc0, 0
	s_lshl_b32 s3, s1, 1
	v_mov_b32_e32 v153, v3
	v_ldexp_f32 v0, v0, s0
	s_lshl_b32 s0, s38, 5
	s_add_i32 s0, s0, s3
	s_or_b32 s8, s0, s63
	s_ashr_i32 s9, s8, 31
	s_lshl_b64 s[28:29], s[8:9], 2
	s_add_u32 s28, s48, s28
	s_addc_u32 s29, s49, s29
	global_load_dword v1, v3, s[28:29]
	s_ashr_i32 s9, s0, 31
	s_lshl_b64 s[8:9], s[8:9], 2
	s_add_u32 s8, s48, s8
	s_addc_u32 s9, s49, s9
	global_load_dword v2, v3, s[8:9] offset:64
	v_mov_b32_e32 v157, v3
	s_movk_i32 s95, 0x6000
	s_waitcnt vmcnt(0)
	v_readfirstlane_b32 s28, v1
	v_readfirstlane_b32 s0, v2
	s_nop 1
	v_mov_b32_e32 v1, s0
	v_mul_f32_e32 v1, s28, v1
	s_mov_b32 s0, 0xf800000
	v_cmp_gt_f32_e32 vcc, s0, v1
	v_mul_f32_e32 v2, 0x4f800000, v1
	s_lshl_b32 s0, s38, 4
	v_cndmask_b32_e32 v1, v1, v2, vcc
	v_sqrt_f32_e32 v2, v1
	s_add_i32 s0, s56, s0
	s_add_i32 s0, s0, s3
	v_add_u32_e32 v4, -1, v2
	v_fma_f32 v5, -v4, v2, v1
	v_cmp_ge_f32_e64 s[8:9], 0, v5
	v_add_u32_e32 v5, 1, v2
	s_nop 0
	v_cndmask_b32_e64 v4, v2, v4, s[8:9]
	v_fma_f32 v2, -v5, v2, v1
	v_cmp_lt_f32_e64 s[8:9], 0, v2
	s_nop 1
	v_cndmask_b32_e64 v2, v4, v5, s[8:9]
	v_mul_f32_e32 v4, 0x37800000, v2
	s_or_b32 s8, s0, s63
	v_cndmask_b32_e32 v2, v2, v4, vcc
	v_mov_b32_e32 v4, 0x260
	s_ashr_i32 s9, s8, 31
	v_cmp_class_f32_e32 vcc, v1, v4
	s_lshl_b64 s[8:9], s[8:9], 2
	s_add_u32 s8, s16, s8
	v_cndmask_b32_e32 v1, v2, v1, vcc
	v_mul_f32_e32 v1, 0x3db504f3, v1
	s_addc_u32 s9, s17, s9
	v_fmamk_f32 v20, v1, 0x3f804189, v195
	s_barrier
; __device__ __forceinline__ void attn_body3(const bf16* __restrict__ Qb, const bf16* __restrict__ Kh, const bf16* __restrict__ Vh,
;                                            bf16* __restrict__ Ob, int seq, int qpos0, float slS, float mraw, char* lds, const int tid) {
;   const int wid = __builtin_amdgcn_readfirstlane(tid >> 6), lane = tid & 63, r32 = lane & 31, hi = lane >> 5;
;   const int pair = wid & 3, role = wid >> 2;
;   constexpr float C = ASCALE * 1.4426950408889634f;
;   f32x16 o[4] = {}; bf16x8 qr[8]; float lsum = 0.f;
;   const int qw0 = qpos0 + pair * QBLK;
;   const float qposf = (float)(qw0 + r32), hi4 = 4.f * (float)hi + 32.f * (float)role;
;   unsigned qa0, qa1, kj0;
;   { const float a1 = bf_lo(cvtpk(slS, 0.f) & 0xffffu), r1 = slS - a1, a2 = bf_lo(cvtpk(r1, 0.f) & 0xffffu), a3 = r1 - a2;
;     const unsigned u12 = cvtpk(a1, a2), u3 = cvtpk(a3, 0.f) & 0xffffu;
;     const unsigned j0 = __float_as_uint((float)(r32 + 32 * role)) >> 16;
;     qa0 = hi ? 0u : u12; qa1 = hi ? 0u : u3; kj0 = hi ? 0u : (j0 | (j0 << 16)); }
;   { const unsigned qoff = (unsigned)((pair * QBLK + r32) * LDQ + hi * 8) * 2u;
; #pragma unroll
;     for (int d0 = 0; d0 < 8; ++d0) qr[d0] = *reinterpret_cast<const bf16x8*>((const char*)Qb + qoff + d0 * 32); }
;   const int vb0 = (int)(uintptr_t)(lds + A3_V) + role * 16384 + v_rd_base(lane);
; __global__ __launch_bounds__(512, 2)
; void hybrid_megakernel(Params p_in) {
;     ...
;           const float Wn = (Bnd + lowb + 104.f) / slope;
;           int t_lo = (int)floorf(fmaxf((float)(qb * 128) - Wn, 0.f) * (1.f / 64.f)) & ~1;
;           int t_hi = (int)fminf(((float)(qb * 128 + 127) + Wn) * (1.f / 64.f) + 1.f, (float)(SEQ / KVBLK));
;           t_hi = min((t_hi + 1) & ~1, SEQ / KVBLK);
;           t_lo = __builtin_amdgcn_readfirstlane(t_lo); t_hi = __builtin_amdgcn_readfirstlane(t_hi);
;           const bf16* Qb = proj + ((long)b * SEQ + qb * 128) * INC + OFF_Q + h * 256 + c * 128;
;           const bf16* Kh = proj + ((long)b * SEQ + t_lo * KVBLK) * INC + OFF_K + h * 256 + c * 128;
;           const bf16* Vh = proj + ((long)b * SEQ + t_lo * KVBLK) * INC + OFF_V + h * 256;
;           bf16* Ob = (bf16*)attO + (long)c * NTOK * 2048 + ((long)b * SEQ + qb * 128) * 2048 + h * 256;
;           __syncthreads();
;           attn_body3(Qb, Kh, Vh, Ob, (t_hi - t_lo) * KVBLK, qb * 128 - t_lo * KVBLK, slope / ASCALE, Bnd / ASCALE, shm, tid);
	s_waitcnt vmcnt(0)
	v_mov_b32_e32 v1, 0x42b20000
	v_div_scale_f32 v2, s[8:9], v0, v0, v1
	v_rcp_f32_e32 v4, v2
	s_lshl_b32 s0, s2, 7
	s_or_b32 s2, s0, 0x7f
	s_lshl_b64 s[8:9], s[38:39], 13
	v_fma_f32 v5, -v2, v4, 1.0
	v_fmac_f32_e32 v4, v5, v4
	v_div_scale_f32 v5, vcc, v1, v0, v1
	v_mul_f32_e32 v6, v5, v4
	v_fma_f32 v7, -v2, v6, v5
	v_fmac_f32_e32 v6, v7, v4
	v_fma_f32 v2, -v2, v6, v5
	v_div_fmas_f32 v2, v2, v4, v6
	v_div_fixup_f32 v1, v2, v0, v1
	v_cvt_f32_u32_e32 v2, s0
	v_cvt_f32_u32_e32 v4, s2
	s_mov_b32 s2, 0x3c800000
	v_sub_f32_e32 v2, v2, v1
	v_max_f32_e32 v2, 0, v2
	v_mul_f32_e32 v2, 0x3c800000, v2
	v_floor_f32_e32 v2, v2
	v_add_f32_e32 v1, v1, v4
	v_fma_f32 v1, v1, s2, 1.0
	v_readfirstlane_b32 s2, v2
	v_min_f32_e32 v1, 0x43000000, v1
	v_cvt_i32_f32_e32 v1, v1
	v_cvt_i32_f32_e32 v2, s2
	v_add_u32_e32 v1, 1, v1
	v_readfirstlane_b32 s2, v2
	s_and_b32 s28, s2, -2
	s_add_u32 s70, s8, s0
	s_addc_u32 s71, s9, 0
	s_mul_i32 s2, s71, 0x6000
	s_mul_hi_u32 s3, s70, 0x6000
	s_add_i32 s3, s3, s2
	s_mul_i32 s2, s70, 0x6000
	s_add_u32 s38, s10, s2
	s_addc_u32 s74, s11, s3
	s_lshl_b32 s2, s1, 8
	s_ashr_i32 s3, s2, 31
	s_lshl_b64 s[72:73], s[2:3], 1
	s_add_u32 s1, s38, s72
	s_addc_u32 s3, s74, s73
	s_lshl_b32 s38, s63, 8
	s_add_u32 s2, s1, s38
	s_addc_u32 s3, s3, 0
	s_lshl_b32 s1, s28, 6
	s_ashr_i32 s74, s1, 31
	s_add_u32 s8, s8, s1
	s_addc_u32 s9, s9, s74
	s_mulk_i32 s9, 0x6000
	s_mul_hi_u32 s74, s8, 0x6000
	s_add_i32 s74, s74, s9
	s_mulk_i32 s8, 0x6000
	s_add_u32 s8, s10, s8
	s_addc_u32 s9, s11, s74
	s_add_u32 s8, s8, s72
	s_addc_u32 s9, s9, s73
	s_add_u32 s38, s8, s38
	s_addc_u32 s75, s9, 0
	v_and_b32_e32 v1, -2, v1
	s_add_u32 s74, s38, 0x1000
	v_min_i32_e32 v1, 0x80, v1
	s_addc_u32 s75, s75, 0
	v_readfirstlane_b32 s29, v1
	s_add_u32 s76, s8, 0x2000
	s_addc_u32 s77, s9, 0
	s_sub_i32 s80, s29, s28
	s_mov_b32 s28, 0x3db504f3
	v_div_scale_f32 v1, s[8:9], s28, s28, v0
	v_rcp_f32_e32 v2, v1
	v_readfirstlane_b32 s8, v144
	s_ashr_i32 s79, s8, 6
	s_and_b32 s81, s79, 3
	v_fma_f32 v4, -v1, v2, 1.0
	v_fmac_f32_e32 v2, v4, v2
	v_div_scale_f32 v4, vcc, v0, s28, v0
	v_mul_f32_e32 v5, v4, v2
	v_fma_f32 v6, -v1, v5, v4
	v_fmac_f32_e32 v5, v6, v2
	v_fma_f32 v1, -v1, v5, v4
	v_div_fmas_f32 v1, v1, v2, v5
	v_div_fixup_f32 v148, v1, s28, v0
	v_cvt_pk_bf16_f32 v0, v148, v3
	s_lshl_b32 s78, s81, 5
	v_lshlrev_b32_e32 v0, 16, v0
	v_sub_f32_e32 v1, v148, v0
	v_cvt_pk_bf16_f32 v2, v1, v3
	s_ashr_i32 s38, s8, 8
	v_lshlrev_b32_e32 v2, 16, v2
	v_sub_f32_e32 v1, v1, v2
	v_cvt_pk_bf16_f32 v0, v0, v2
	v_or_b32_e32 v2, s78, v149
	v_mul_u32_u24_e32 v2, 0x6000, v2
	v_or_b32_e32 v2, v2, v165
	v_cvt_pk_bf16_f32 v1, v1, v3
	global_load_dwordx4 v[96:99], v2, s[2:3]
	global_load_dwordx4 v[100:103], v2, s[2:3] offset:32
	global_load_dwordx4 v[104:107], v2, s[2:3] offset:64
	global_load_dwordx4 v[108:111], v2, s[2:3] offset:96
	global_load_dwordx4 v[112:115], v2, s[2:3] offset:128
	global_load_dwordx4 v[116:119], v2, s[2:3] offset:160
	global_load_dwordx4 v[120:123], v2, s[2:3] offset:192
	global_load_dwordx4 v[124:127], v2, s[2:3] offset:224
	s_lshl_b32 s2, s79, 7
	v_or_b32_e32 v2, s2, v145
	s_ashr_i32 s2, s2, 4
	s_and_b32 s3, s2, 0x7fff0
	s_lshr_b32 s2, s2, 1
	v_or_b32_e32 v4, s3, v174
	v_and_or_b32 v4, s2, 4, v4
	v_ashrrev_i32_e32 v5, 4, v2
	s_movk_i32 s2, 0x6000
	v_mul_lo_u32 v6, v5, s2
	v_bitop3_b32 v5, v5, v173, 3 bitop3:0x6c
	v_or_b32_e32 v2, 64, v2
	v_lshl_or_b32 v150, v5, 4, v6
	v_ashrrev_i32_e32 v5, 4, v2
	v_mul_lo_u32 v6, v5, s2
	s_movk_i32 s2, 0x60
	v_and_or_b32 v2, v2, s2, v175
	s_lshl_b32 s2, s79, 11
	s_add_i32 s83, s2, 0
	s_add_i32 s84, s83, 0x18000
	v_bitop3_b32 v5, v5, v173, 7 bitop3:0x6c
	s_mov_b32 m0, s84
	s_add_i32 s85, s83, 0x18400
	v_mul_u32_u24_e32 v4, 0x6000, v4
	v_lshl_or_b32 v154, v5, 4, v6
	global_load_lds_dwordx4 v150, s[74:75]
	s_mov_b32 m0, s85
	v_or_b32_e32 v152, v4, v176
	global_load_lds_dwordx4 v154, s[74:75]
	s_mov_b32 m0, s83
	v_lshl_or_b32 v156, v2, 1, v4
	v_lshl_add_u64 v[4:5], s[76:77], 0, v[152:153]
	global_load_lds_dwordx4 v152, s[76:77]
	s_add_i32 m0, s83, 0x400
	v_lshl_add_u64 v[6:7], s[76:77], 0, v[156:157]
	global_load_lds_dwordx4 v156, s[76:77]
	v_lshl_add_u64 v[4:5], v[4:5], 0, s[42:43]
	s_add_i32 m0, s83, 0x4000
	s_lshl_b32 s82, s38, 5
	global_load_lds_dwordx4 v[4:5], off
	v_lshl_add_u64 v[4:5], v[6:7], 0, s[42:43]
	s_add_i32 m0, s83, 0x4400
	v_or_b32_e32 v147, s82, v149
	global_load_lds_dwordx4 v[4:5], off
	s_waitcnt vmcnt(0)
	v_lshl_add_u32 v179, s81, 12, v168
	v_lshl_add_u32 v180, s38, 14, v167
	s_cmp_lt_i32 s80, 1
	s_waitcnt vmcnt(0) lgkmcnt(0)
	s_barrier
	s_cbranch_scc1 .LBB0_186
	v_mov_b32_e32 v151, v3
	v_mov_b32_e32 v155, v3
	s_lshl_b32 s29, s80, 6
	s_cmpk_lt_u32 s29, 0x80
	s_cbranch_scc1 .LBB0_160
	s_add_u32 s2, s76, 0x180000
	s_addc_u32 s3, s77, 0
	s_add_u32 s8, s74, 0x180000
	s_addc_u32 s9, s75, 0
	v_lshl_add_u64 v[4:5], s[8:9], 0, v[150:151]
	s_add_i32 m0, s83, 0x1c000
	s_nop 0
	global_load_lds_dwordx4 v[4:5], off
	v_lshl_add_u64 v[4:5], s[8:9], 0, v[154:155]
	s_add_i32 m0, s83, 0x1c400
	s_nop 0
	global_load_lds_dwordx4 v[4:5], off
	v_lshl_add_u64 v[4:5], s[2:3], 0, v[152:153]
	s_add_i32 m0, s83, 0x8000
	s_nop 0
	global_load_lds_dwordx4 v[4:5], off
	s_add_i32 m0, s83, 0x8400
	v_lshl_add_u64 v[4:5], s[2:3], 0, v[156:157]
	s_add_u32 s2, s76, 0x180100
	s_addc_u32 s3, s77, 0
	global_load_lds_dwordx4 v[4:5], off
	v_lshl_add_u64 v[4:5], s[2:3], 0, v[152:153]
	s_add_i32 m0, s83, 0xc000
	s_nop 0
	global_load_lds_dwordx4 v[4:5], off
	v_lshl_add_u64 v[4:5], s[2:3], 0, v[156:157]
	s_add_i32 m0, s83, 0xc400
	s_nop 0
	global_load_lds_dwordx4 v[4:5], off

.LBB0_164:
	s_mov_b32 s2, 0x3db504f3
	v_div_scale_f32 v1, s[0:1], s2, s2, v20
	v_rcp_f32_e32 v2, v1
	v_add_u32_e32 v202, 0x20000, v179
	s_lshl_b32 s28, s38, 11
	v_add_u32_e32 v204, s28, v202
	v_fma_f32 v21, -v1, v2, 1.0
	v_fmac_f32_e32 v2, v21, v2
	v_div_scale_f32 v21, vcc, v20, s2, v20
	v_mul_f32_e32 v22, v21, v2
	v_fma_f32 v23, -v1, v22, v21
	v_fmac_f32_e32 v22, v23, v2
	v_fma_f32 v1, -v1, v22, v21
	v_div_fmas_f32 v1, v1, v2, v22
	v_div_fixup_f32 v203, v1, s2, v20
	v_sub_f32_e32 v0, v0, v203
	v_mul_f32_e32 v0, 0x3e0293ee, v0
	v_fmamk_f32 v1, v4, 0x3e0293ee, v0
	v_exp_f32_e32 v24, v1
	v_fmamk_f32 v1, v5, 0x3e0293ee, v0
	v_exp_f32_e32 v25, v1
	v_fmamk_f32 v1, v6, 0x3e0293ee, v0
	v_exp_f32_e32 v26, v1
	v_fmamk_f32 v1, v7, 0x3e0293ee, v0
	v_exp_f32_e32 v27, v1
	v_fmamk_f32 v1, v8, 0x3e0293ee, v0
	v_exp_f32_e32 v28, v1
	v_fmamk_f32 v1, v9, 0x3e0293ee, v0
	v_exp_f32_e32 v29, v1
	v_fmamk_f32 v1, v10, 0x3e0293ee, v0
	v_exp_f32_e32 v30, v1
	v_fmamk_f32 v1, v11, 0x3e0293ee, v0
	v_exp_f32_e32 v31, v1
	v_fmamk_f32 v1, v12, 0x3e0293ee, v0
	v_exp_f32_e32 v32, v1
	v_fmamk_f32 v1, v13, 0x3e0293ee, v0
	v_exp_f32_e32 v33, v1
	v_fmamk_f32 v1, v14, 0x3e0293ee, v0
	v_exp_f32_e32 v34, v1
	v_fmamk_f32 v1, v15, 0x3e0293ee, v0
	v_exp_f32_e32 v35, v1
	v_fmamk_f32 v1, v16, 0x3e0293ee, v0
	v_exp_f32_e32 v36, v1
	v_fmamk_f32 v1, v17, 0x3e0293ee, v0
	v_cvt_pk_bf16_f32 v4, v24, v25
	v_cvt_pk_bf16_f32 v5, v26, v27
	v_cvt_pk_bf16_f32 v6, v28, v29
	v_cvt_pk_bf16_f32 v7, v30, v31
	v_exp_f32_e32 v37, v1
	v_fmamk_f32 v1, v18, 0x3e0293ee, v0
	v_fmac_f32_e32 v0, 0x3e0293ee, v19
	v_permlane32_swap_b32_e32 v4, v6
	v_permlane32_swap_b32_e32 v5, v7
	v_exp_f32_e32 v38, v1
	v_exp_f32_e32 v39, v0
	ds_write_b128 v204, v[4:7]
	v_cvt_pk_bf16_f32 v4, v32, v33
	v_cvt_pk_bf16_f32 v5, v34, v35
	v_cvt_pk_bf16_f32 v6, v36, v37
	v_cvt_pk_bf16_f32 v7, v38, v39
	s_nop 0
	v_permlane32_swap_b32_e32 v4, v6
	v_permlane32_swap_b32_e32 v5, v7
	ds_write_b128 v204, v[4:7] offset:1024
	s_waitcnt vmcnt(4) lgkmcnt(0)
	s_barrier
	s_cmpk_gt_u32 s29, 0xbf
	s_cselect_b64 s[2:3], -1, 0
	s_cmpk_lt_u32 s29, 0xc0
	s_cbranch_scc1 .LBB0_166
	s_add_u32 s0, s76, 0x300000
	s_addc_u32 s1, s77, 0
	s_add_u32 s8, s74, 0x300000
	s_addc_u32 s9, s75, 0
	s_mov_b32 m0, s84
	v_lshl_add_u64 v[0:1], s[8:9], 0, v[150:151]
	s_add_i32 s29, s83, 0x10000
	global_load_lds_dwordx4 v[0:1], off
	v_lshl_add_u64 v[0:1], s[8:9], 0, v[154:155]
	s_mov_b32 m0, s85
	s_nop 0
	global_load_lds_dwordx4 v[0:1], off
	v_lshl_add_u64 v[0:1], s[0:1], 0, v[152:153]
	s_mov_b32 m0, s29
	s_nop 0
	global_load_lds_dwordx4 v[0:1], off
	s_add_i32 m0, s83, 0x10400
	v_lshl_add_u64 v[0:1], s[0:1], 0, v[156:157]
	s_add_u32 s0, s76, 0x300100
	s_addc_u32 s1, s77, 0
	global_load_lds_dwordx4 v[0:1], off
	v_lshl_add_u64 v[0:1], s[0:1], 0, v[152:153]
	s_add_i32 m0, s83, 0x14000
	s_nop 0
	global_load_lds_dwordx4 v[0:1], off
	v_lshl_add_u64 v[0:1], s[0:1], 0, v[156:157]
	s_add_i32 m0, s83, 0x14400
	s_nop 0
	global_load_lds_dwordx4 v[0:1], off
